# best4 + nt on all dwordx4 loads of ssm pass1/pass2
# speedup vs baseline: 1.0047x; 1.0047x over previous
; __device__ __forceinline__ void ssm2_coef(const Ctx& c, int l, int g, int p, int hi, float& ar, float& ai, float (&br)[8], float (&bi)[8]) {
;     const int gp = (l * 16 + g) * 64 + p;
;     const float are = c.inp(IN_ARE)[gp], aim = c.inp(IN_AIM)[gp], dt = expf(c.inp(IN_LOGDT)[l * 16 + g]);
;     const float mag = expf(are * dt), ang = aim * dt;
;     ar = mag * cosf(ang); ai = mag * sinf(ang);
;     const float den = are * are + aim * aim, nr = ar - 1.0f;
;     const float cr = (nr * are + ai * aim) / den, ci = (ai * are - nr * aim) / den;
;     const f32x4* pr = (const f32x4*)(c.inp(IN_BRE) + (size_t)gp * 16 + 8 * hi); const f32x4* pi = (const f32x4*)(c.inp(IN_BIM) + (size_t)gp * 16 + 8 * hi);
; #pragma unroll
;     for (int q4 = 0; q4 < 2; ++q4) { const f32x4 r4 = pr[q4], i4 = pi[q4];
.LBB0_110:
	s_or_b64 exec, exec, s[42:43]
	v_lshlrev_b64 v[2:3], 6, v[16:17]
	global_load_dword v64, v[0:1], off offset:128
	v_lshl_add_u64 v[6:7], v[140:141], 0, v[2:3]
	v_lshl_add_u64 v[12:13], v[142:143], 0, v[2:3]
	global_load_dwordx4 v[0:3], v[6:7], off offset:16 nt
	global_load_dwordx4 v[8:11], v[6:7], off nt
	global_load_dword v66, v[4:5], off offset:128
	s_nop 0
	global_load_dwordx4 v[4:7], v[12:13], off offset:16 nt
	s_nop 0
	global_load_dwordx4 v[12:15], v[12:13], off nt
	s_brev_b32 s22, 18
	s_waitcnt vmcnt(5)
	v_mul_f32_e32 v73, v68, v64
	v_and_b32_e32 v74, 0x7fffffff, v73
	v_lshrrev_b32_e32 v17, 23, v74
	v_and_b32_e32 v19, 0x7fffff, v74
	v_cmp_nlt_f32_e64 s[52:53], |v73|, s22
	v_add_u32_e32 v18, 0xffffff88, v17
	v_or_b32_e32 v17, 0x800000, v19
	s_and_saveexec_b64 s[42:43], s[52:53]
	s_xor_b64 s[54:55], exec, s[42:43]
	s_cbranch_execz .LBB0_112
	v_cmp_lt_u32_e32 vcc, 63, v18
	s_mov_b32 s22, 0xfe5163ab
	v_mov_b32_e32 v23, v97
	v_cndmask_b32_e32 v19, 0, v224, vcc
	v_add_u32_e32 v19, v19, v18
	v_cmp_lt_u32_e64 s[42:43], 31, v19
	v_mov_b32_e32 v25, v97
	v_mov_b32_e32 v27, v97
	v_cndmask_b32_e64 v20, 0, v225, s[42:43]
	v_add_u32_e32 v19, v20, v19
	v_cmp_lt_u32_e64 s[44:45], 31, v19
	v_mov_b32_e32 v29, v97
	v_mov_b32_e32 v31, v97
	v_cndmask_b32_e64 v20, 0, v225, s[44:45]
	v_add_u32_e32 v19, v20, v19
	v_mad_u64_u32 v[20:21], s[46:47], v17, s22, 0
	v_mov_b32_e32 v22, v21
	s_mov_b32 s22, 0x3c439041
	v_mad_u64_u32 v[22:23], s[46:47], v17, s22, v[22:23]
	v_mov_b32_e32 v24, v23
	s_mov_b32 s22, 0xdb629599
	v_mad_u64_u32 v[24:25], s[46:47], v17, s22, v[24:25]
	v_mov_b32_e32 v26, v25
	s_mov_b32 s22, 0xf534ddc0
	v_mad_u64_u32 v[26:27], s[46:47], v17, s22, v[26:27]
	v_mov_b32_e32 v28, v27
	s_mov_b32 s22, 0xfc2757d1
	v_mad_u64_u32 v[28:29], s[46:47], v17, s22, v[28:29]
	v_mov_b32_e32 v30, v29
	s_mov_b32 s22, 0x4e441529
	v_mad_u64_u32 v[30:31], s[46:47], v17, s22, v[30:31]
	v_mov_b32_e32 v32, v31
	v_mov_b32_e32 v33, v97
	s_mov_b32 s22, 0xa2f9836e
	v_mad_u64_u32 v[32:33], s[46:47], v17, s22, v[32:33]
	v_cndmask_b32_e32 v21, v30, v26, vcc
	v_cndmask_b32_e32 v23, v32, v28, vcc
	v_cndmask_b32_e32 v27, v33, v30, vcc
	v_cndmask_b32_e64 v25, v23, v21, s[42:43]
	v_cndmask_b32_e64 v23, v27, v23, s[42:43]
	v_cndmask_b32_e32 v27, v28, v24, vcc
	v_cndmask_b32_e64 v21, v21, v27, s[42:43]
	v_cndmask_b32_e64 v23, v23, v25, s[44:45]
	v_cndmask_b32_e64 v25, v25, v21, s[44:45]
	v_sub_u32_e32 v28, 32, v19
	v_alignbit_b32 v29, v23, v25, v28
	v_cmp_eq_u32_e64 s[46:47], 0, v19
	v_cndmask_b32_e32 v22, v26, v22, vcc
	v_cndmask_b32_e32 v20, v24, v20, vcc
	v_cndmask_b32_e64 v19, v29, v23, s[46:47]
	v_cndmask_b32_e64 v23, v27, v22, s[42:43]
	v_cndmask_b32_e64 v21, v21, v23, s[44:45]
	v_alignbit_b32 v26, v25, v21, v28
	v_cndmask_b32_e64 v25, v26, v25, s[46:47]
	v_bfe_u32 v29, v19, 29, 1
	v_cndmask_b32_e64 v20, v22, v20, s[42:43]
	v_alignbit_b32 v26, v19, v25, 30
	v_sub_u32_e32 v30, 0, v29
	v_cndmask_b32_e64 v20, v23, v20, s[44:45]
	v_xor_b32_e32 v26, v26, v30
	v_alignbit_b32 v22, v21, v20, v28
	v_cndmask_b32_e64 v21, v22, v21, s[46:47]
	v_ffbh_u32_e32 v23, v26
	v_alignbit_b32 v22, v25, v21, 30
	v_min_u32_e32 v23, 32, v23
	v_alignbit_b32 v20, v21, v20, 30
	v_xor_b32_e32 v22, v22, v30
	v_sub_u32_e32 v24, 31, v23
	v_xor_b32_e32 v20, v20, v30
	v_alignbit_b32 v25, v26, v22, v24
	v_alignbit_b32 v20, v22, v20, v24
	v_alignbit_b32 v21, v25, v20, 9
	v_ffbh_u32_e32 v22, v21
	v_min_u32_e32 v22, 32, v22
	v_lshrrev_b32_e32 v27, 29, v19
	v_not_b32_e32 v24, v22
	v_alignbit_b32 v20, v21, v20, v24
	v_lshlrev_b32_e32 v21, 31, v27
	v_or_b32_e32 v24, 0x33000000, v21
	v_add_lshl_u32 v22, v22, v23, 23
	v_lshrrev_b32_e32 v20, 9, v20
	v_sub_u32_e32 v22, v24, v22
	v_or_b32_e32 v21, 0.5, v21
	v_lshlrev_b32_e32 v23, 23, v23
	v_or_b32_e32 v20, v22, v20
	v_lshrrev_b32_e32 v22, 9, v25
	v_sub_u32_e32 v21, v21, v23
	v_or_b32_e32 v21, v22, v21
	v_mul_f32_e32 v22, 0x3fc90fda, v21
	s_mov_b32 s22, 0x3fc90fda
	v_fma_f32 v23, v21, s22, -v22
	v_fmac_f32_e32 v23, 0x33a22168, v21
	v_fmac_f32_e32 v23, 0x3fc90fda, v20
	v_lshrrev_b32_e32 v19, 30, v19
	v_add_f32_e32 v76, v22, v23
	v_add_u32_e32 v75, v29, v19

; __device__ __forceinline__ void ssm2_coef(const Ctx& c, int l, int g, int p, int hi, float& ar, float& ai, float (&br)[8], float (&bi)[8]) {
;     ...
;     const float are = c.inp(IN_ARE)[gp], aim = c.inp(IN_AIM)[gp], dt = expf(c.inp(IN_LOGDT)[l * 16 + g]);
;     const float mag = expf(are * dt), ang = aim * dt;
;     ar = mag * cosf(ang); ai = mag * sinf(ang);
;     const float den = are * are + aim * aim, nr = ar - 1.0f;
;     const float cr = (nr * are + ai * aim) / den, ci = (ai * are - nr * aim) / den;
;     const f32x4* pr = (const f32x4*)(c.inp(IN_BRE) + (size_t)gp * 16 + 8 * hi); const f32x4* pi = (const f32x4*)(c.inp(IN_BIM) + (size_t)gp * 16 + 8 * hi);
; #pragma unroll
;     for (int q4 = 0; q4 < 2; ++q4) { const f32x4 r4 = pr[q4], i4 = pi[q4];
; #pragma unroll
;         for (int i = 0; i < 4; ++i) { br[4 * q4 + i] = cr * r4[i] - ci * i4[i]; bi[4 * q4 + i] = cr * i4[i] + ci * r4[i]; } }
; template <bool PASS2> __device__ __forceinline__ void ssm2_pass(const Ctx& c, int l) {
;     ...
;           ssm2_coef(c, l, g, q, hi, arA, aiA, t0, t1); split_bf16x8(t0, Bh[0], Bl[0]); split_bf16x8(t1, Bh[2], Bl[2]);
;           ssm2_coef(c, l, g, 32 + q, hi, arB, aiB, t0, t1); split_bf16x8(t0, Bh[1], Bl[1]); split_bf16x8(t1, Bh[3], Bl[3]); }
;         bf16x8 Cb[8]; float dsk = 0.f;
;         if (PASS2) { const int h = lane & 15, kq = 4 * (lane >> 4); const size_t cb = ((size_t)(l * 16 + g) * 16 + h) * 64;
; #pragma unroll
;             for (int s_ = 0; s_ < 8; ++s_) { const float* src = (s_ < 4 ? c.inp(IN_CRE) : c.inp(IN_CIM)) + cb + 16 * (s_ & 3) + kq; const float sg = (s_ < 4) ? 1.f : -1.f;
;                 const f32x4 v0 = *(const f32x4*)src;
;                 const u32x4 w = {pk_bf16(sg * v0[0], sg * v0[0]), pk_bf16(sg * v0[1], sg * v0[1]), pk_bf16(sg * v0[2], sg * v0[2]), pk_bf16(sg * v0[3], sg * v0[3])};
;                 Cb[s_] = __builtin_bit_cast(bf16x8, w); }
;             dsk = c.inp(IN_DSKIP)[l * 256 + g * 16 + h]; }
;         float xAr = 0.f, xAi = 0.f, xBr = 0.f, xBi = 0.f;
;         if (PASS2 && tk > 0) {
;             float pAr = arA, pAi = aiA, pBr = arB, pBi = aiB;
; #pragma unroll
;             for (int k = 0; k < 8; ++k) { float nr = pAr * pAr - pAi * pAi, ni = 2.f * pAr * pAi; pAr = nr; pAi = ni; nr = pBr * pBr - pBi * pBi; ni = 2.f * pBr * pBi; pBr = nr; pBi = ni; }
.LBB0_118:
	s_or_b64 exec, exec, s[42:43]
	s_waitcnt vmcnt(2)
	v_mul_f32_e32 v17, v68, v66
	v_mul_f32_e32 v18, 0x3fb8aa3b, v17
	v_fma_f32 v19, v17, s48, -v18
	v_rndne_f32_e32 v20, v18
	v_fmac_f32_e32 v19, 0x32a5705f, v17
	v_sub_f32_e32 v18, v18, v20
	v_add_f32_e32 v18, v18, v19
	v_exp_f32_e32 v18, v18
	v_cvt_i32_f32_e32 v19, v20
	v_cmp_ngt_f32_e32 vcc, s49, v17
	s_mov_b32 s22, 0x42b17218
	v_or_b32_e32 v16, 32, v16
	v_ldexp_f32 v18, v18, v19
	v_cndmask_b32_e32 v18, 0, v18, vcc
	v_cmp_nlt_f32_e32 vcc, s22, v17
	v_mul_f32_e32 v17, v76, v76
	s_lshl_b64 s[42:43], s[50:51], 12
	v_cndmask_b32_e32 v79, v223, v18, vcc
	v_fmamk_f32 v18, v17, 0xb94c1982, v215
	v_fmaak_f32 v18, v17, v18, 0xbe2aaa9d
	v_mul_f32_e32 v18, v17, v18
	v_fmac_f32_e32 v76, v76, v18
	v_fmamk_f32 v18, v17, 0x37d75334, v216
	v_fmaak_f32 v18, v17, v18, 0x3d2aabf7
	v_fmaak_f32 v18, v17, v18, 0xbf000004
	v_fma_f32 v82, v17, v18, 1.0
	v_ashrrev_i32_e32 v17, 31, v16
	v_lshlrev_b64 v[16:17], 6, v[16:17]
	v_lshl_add_u64 v[18:19], v[140:141], 0, v[16:17]
	v_lshl_add_u64 v[16:17], v[142:143], 0, v[16:17]
	global_load_dwordx4 v[48:51], v[18:19], off offset:16 nt
	global_load_dwordx4 v[56:59], v[18:19], off nt
	global_load_dwordx4 v[52:55], v[16:17], off offset:16 nt
	global_load_dwordx4 v[60:63], v[16:17], off nt
	v_lshl_add_u64 v[16:17], v[144:145], 0, s[42:43]
	s_lshl_b32 s6, s6, 4
	global_load_dwordx4 v[44:47], v[16:17], off nt
	global_load_dwordx4 v[40:43], v[16:17], off offset:64 nt
	global_load_dwordx4 v[36:39], v[16:17], off offset:128 nt
	global_load_dwordx4 v[32:35], v[16:17], off offset:192 nt
	v_lshl_add_u64 v[16:17], v[146:147], 0, s[42:43]
	v_or_b32_e32 v80, s6, v139
	global_load_dwordx4 v[28:31], v[16:17], off nt
	global_load_dwordx4 v[24:27], v[16:17], off offset:64 nt
	global_load_dwordx4 v[20:23], v[16:17], off offset:128 nt
	s_nop 0
	global_load_dwordx4 v[16:19], v[16:17], off offset:192 nt
	v_ashrrev_i32_e32 v81, 31, v80
	v_lshl_add_u64 v[80:81], v[80:81], 2, s[74:75]
	global_load_dword v178, v[80:81], off
	v_and_b32_e32 v80, 1, v75
	v_cmp_eq_u32_e32 vcc, 0, v80
	v_lshlrev_b32_e32 v75, 30, v75
	s_brev_b32 s24, 1
	v_cndmask_b32_e64 v76, -v76, v82, vcc
	v_mul_f32_e32 v68, v114, v68
	v_bitop3_b32 v75, v75, v76, s24 bitop3:0x6c
	v_mul_f32_e32 v76, 0x3fb8aa3b, v68
	v_fma_f32 v80, v68, s48, -v76
	v_rndne_f32_e32 v81, v76
	v_fmac_f32_e32 v80, 0x32a5705f, v68
	v_sub_f32_e32 v76, v76, v81
	v_add_f32_e32 v76, v76, v80
	v_exp_f32_e32 v76, v76
	v_cvt_i32_f32_e32 v80, v81
	s_movk_i32 s25, 0x1f8
	v_cmp_class_f32_e64 vcc, v73, s25
	v_cmp_ngt_f32_e64 s[42:43], s49, v68
	s_lshr_b32 s31, s17, 4
	v_cndmask_b32_e32 v75, v226, v75, vcc
	v_mul_f32_e32 v157, v79, v75
	v_ldexp_f32 v75, v76, v80
	v_cndmask_b32_e64 v75, 0, v75, s[42:43]
	v_cmp_nlt_f32_e64 s[42:43], s22, v68
	s_and_b32 s22, s17, 15
	s_cmp_lg_u32 s22, 0
	v_cndmask_b32_e64 v68, v223, v75, s[42:43]
	v_mul_f32_e32 v75, v70, v70
	v_fmamk_f32 v76, v75, 0xb94c1982, v215
	v_fmaak_f32 v76, v75, v76, 0xbe2aaa9d
	v_mul_f32_e32 v76, v75, v76
	v_fmac_f32_e32 v70, v70, v76
	v_fmamk_f32 v76, v75, 0x37d75334, v216
	v_fmaak_f32 v76, v75, v76, 0x3d2aabf7
	v_fmaak_f32 v76, v75, v76, 0xbf000004
	v_fma_f32 v75, v75, v76, 1.0
	v_and_b32_e32 v76, 1, v69
	v_cmp_eq_u32_e64 s[42:43], 0, v76
	v_lshlrev_b32_e32 v69, 30, v69
	s_nop 0
	v_cndmask_b32_e64 v70, -v70, v75, s[42:43]
	v_bitop3_b32 v69, v69, v70, s24 bitop3:0x6c
	v_cmp_class_f32_e64 s[42:43], v65, s25
	v_xor_b32_e32 v65, v67, v65
	s_nop 0
	v_cndmask_b32_e64 v69, v226, v69, s[42:43]
	v_mul_f32_e32 v156, v68, v69
	v_mul_f32_e32 v69, v72, v72
	v_fmamk_f32 v70, v69, 0xb94c1982, v215
	v_fmaak_f32 v70, v69, v70, 0xbe2aaa9d
	v_mul_f32_e32 v70, v69, v70
	v_fmac_f32_e32 v72, v72, v70
	v_fmamk_f32 v70, v69, 0x37d75334, v216
	v_fmaak_f32 v70, v69, v70, 0x3d2aabf7
	v_fmaak_f32 v70, v69, v70, 0xbf000004
	v_fma_f32 v69, v69, v70, 1.0
	v_and_b32_e32 v70, 1, v71
	v_cmp_eq_u32_e64 s[44:45], 0, v70
	v_lshlrev_b32_e32 v70, 30, v71
	v_and_b32_e32 v70, 0x80000000, v70
	v_cndmask_b32_e64 v69, v69, v72, s[44:45]
	v_xor_b32_e32 v65, v65, v70
	v_xor_b32_e32 v65, v65, v69
	v_cndmask_b32_e64 v65, v226, v65, s[42:43]
	v_mul_f32_e32 v118, v68, v65
	v_mul_f32_e32 v65, v78, v78
	v_fmamk_f32 v67, v65, 0xb94c1982, v215
	v_fmaak_f32 v67, v65, v67, 0xbe2aaa9d
	v_mul_f32_e32 v67, v65, v67
	v_fmac_f32_e32 v78, v78, v67
	v_fmamk_f32 v67, v65, 0x37d75334, v216
	v_fmaak_f32 v67, v65, v67, 0x3d2aabf7
	v_fmaak_f32 v67, v65, v67, 0xbf000004
	v_fma_f32 v65, v65, v67, 1.0
	v_and_b32_e32 v67, 1, v77
	v_cmp_eq_u32_e64 s[42:43], 0, v67
	v_lshlrev_b32_e32 v67, 30, v77
	v_and_b32_e32 v67, 0x80000000, v67
	v_xor_b32_e32 v68, v74, v73
	v_cndmask_b32_e64 v65, v65, v78, s[42:43]
	v_xor_b32_e32 v67, v68, v67
	v_xor_b32_e32 v65, v67, v65
	v_cndmask_b32_e32 v65, v226, v65, vcc
	v_mul_f32_e32 v68, v79, v65
	s_cbranch_scc0 .LBB0_191
	v_mov_b32_e32 v119, v68
	v_pk_add_f32 v[74:75], v[156:157], v[156:157]
	v_pk_mul_f32 v[72:73], v[118:119], v[118:119]
	v_pk_mul_f32 v[74:75], v[74:75], v[118:119]
	v_pk_fma_f32 v[72:73], v[156:157], v[156:157], v[72:73] neg_lo:[0,0,1] neg_hi:[0,0,1]
	v_pk_mul_f32 v[76:77], v[74:75], v[74:75]
	s_lshl_b32 s42, s31, 4
	v_pk_fma_f32 v[76:77], v[72:73], v[72:73], v[76:77] neg_lo:[0,0,1] neg_hi:[0,0,1]
	v_pk_add_f32 v[72:73], v[72:73], v[72:73]
	s_ashr_i32 s43, s42, 31
	v_pk_mul_f32 v[72:73], v[74:75], v[72:73]
	s_lshl_b64 s[42:43], s[42:43], 9
	v_pk_mul_f32 v[74:75], v[72:73], v[72:73]
	v_mov_b32_e32 v166, 0
	v_pk_fma_f32 v[74:75], v[76:77], v[76:77], v[74:75] neg_lo:[0,0,1] neg_hi:[0,0,1]
	v_pk_add_f32 v[76:77], v[76:77], v[76:77]
	s_and_b32 s34, s21, 15
	v_pk_mul_f32 v[72:73], v[72:73], v[76:77]
	v_lshl_add_u64 v[70:71], v[148:149], 0, s[42:43]
	v_pk_mul_f32 v[76:77], v[72:73], v[72:73]
	v_mov_b64_e32 v[158:159], v[118:119]
	v_pk_fma_f32 v[76:77], v[74:75], v[74:75], v[76:77] neg_lo:[0,0,1] neg_hi:[0,0,1]
	v_pk_add_f32 v[74:75], v[74:75], v[74:75]
	v_mov_b32_e32 v167, v166
	v_pk_mul_f32 v[72:73], v[72:73], v[74:75]
	v_mov_b32_e32 v168, v166
	v_pk_mul_f32 v[74:75], v[72:73], v[72:73]
	v_mov_b32_e32 v169, v166
	v_pk_fma_f32 v[74:75], v[76:77], v[76:77], v[74:75] neg_lo:[0,0,1] neg_hi:[0,0,1]
	v_pk_add_f32 v[76:77], v[76:77], v[76:77]
	s_nop 0
	v_pk_mul_f32 v[72:73], v[72:73], v[76:77]
	s_nop 0
	v_pk_mul_f32 v[76:77], v[72:73], v[72:73]
	s_nop 0
	v_pk_fma_f32 v[76:77], v[74:75], v[74:75], v[76:77] neg_lo:[0,0,1] neg_hi:[0,0,1]
	v_pk_add_f32 v[74:75], v[74:75], v[74:75]
	s_nop 0
	v_pk_mul_f32 v[72:73], v[72:73], v[74:75]
	s_nop 0
	v_pk_mul_f32 v[74:75], v[72:73], v[72:73]
	s_nop 0
	v_pk_fma_f32 v[74:75], v[76:77], v[76:77], v[74:75] neg_lo:[0,0,1] neg_hi:[0,0,1]
	v_pk_add_f32 v[76:77], v[76:77], v[76:77]
	v_pk_add_f32 v[78:79], v[74:75], v[74:75]
	v_pk_mul_f32 v[76:77], v[72:73], v[76:77]
	s_nop 0
	v_pk_mul_f32 v[72:73], v[76:77], v[76:77]
	s_nop 0
	v_pk_fma_f32 v[72:73], v[74:75], v[74:75], v[72:73] neg_lo:[0,0,1] neg_hi:[0,0,1]
	v_pk_mul_f32 v[74:75], v[76:77], v[78:79]

; __device__ __forceinline__ float bf_lo(unsigned w) { return __uint_as_float(w << 16); }
; __device__ __forceinline__ float bf_hi(unsigned w) { return __uint_as_float(w & 0xffff0000u); }
; __device__ __forceinline__ unsigned pk_bf16(float lo, float hi) { return pg8::cvt_pk_bf16(lo, hi); }
; __device__ __forceinline__ void ssm2_coef(const Ctx& c, int l, int g, int p, int hi, float& ar, float& ai, float (&br)[8], float (&bi)[8]) {
;     ...
;     const float den = are * are + aim * aim, nr = ar - 1.0f;
;     const float cr = (nr * are + ai * aim) / den, ci = (ai * are - nr * aim) / den;
;     const f32x4* pr = (const f32x4*)(c.inp(IN_BRE) + (size_t)gp * 16 + 8 * hi); const f32x4* pi = (const f32x4*)(c.inp(IN_BIM) + (size_t)gp * 16 + 8 * hi);
; #pragma unroll
;     for (int q4 = 0; q4 < 2; ++q4) { const f32x4 r4 = pr[q4], i4 = pi[q4];
; #pragma unroll
;         for (int i = 0; i < 4; ++i) { br[4 * q4 + i] = cr * r4[i] - ci * i4[i]; bi[4 * q4 + i] = cr * i4[i] + ci * r4[i]; } }
; }
; __device__ __forceinline__ void split_bf16x8(const float (&v)[8], bf16x8& hi8, bf16x8& lo8) {
;     u32x4 hw, lw;
; #pragma unroll
;     for (int k = 0; k < 4; ++k) { const unsigned h = pk_bf16(v[2 * k], v[2 * k + 1]); const unsigned lo = pk_bf16(v[2 * k] - bf_lo(h), v[2 * k + 1] - bf_hi(h)); hw[k] = h; lw[k] = lo; }
;     hi8 = __builtin_bit_cast(bf16x8, hw); lo8 = __builtin_bit_cast(bf16x8, lw);
; template <bool PASS2> __device__ __forceinline__ void ssm2_pass(const Ctx& c, int l) {
;     ...
;             for (int s_ = 0; s_ < 8; ++s_) { const float* src = (s_ < 4 ? c.inp(IN_CRE) : c.inp(IN_CIM)) + cb + 16 * (s_ & 3) + kq; const float sg = (s_ < 4) ? 1.f : -1.f;
;                 const f32x4 v0 = *(const f32x4*)src;
;                 const u32x4 w = {pk_bf16(sg * v0[0], sg * v0[0]), pk_bf16(sg * v0[1], sg * v0[1]), pk_bf16(sg * v0[2], sg * v0[2]), pk_bf16(sg * v0[3], sg * v0[3])};
;                 Cb[s_] = __builtin_bit_cast(bf16x8, w); }
.LBB0_123:
	v_mov_b32_e32 v69, v64
	v_add_f32_e32 v70, -1.0, v157
	v_mov_b32_e32 v71, v66
	v_pk_mul_f32 v[72:73], v[64:65], v[68:69] op_sel_hi:[0,1]
	v_pk_fma_f32 v[72:73], v[66:67], v[70:71], v[72:73] op_sel_hi:[0,1,1]
	v_div_scale_f32 v65, s[42:43], v73, v73, v72
	v_rcp_f32_e32 v67, v65
	s_waitcnt vmcnt(1)
	v_xor_b32_e32 v16, 0x80000000, v16
	v_cvt_pk_bf16_f32 v110, v16, v16
	v_xor_b32_e32 v16, 0x80000000, v17
	v_fma_f32 v69, -v65, v67, 1.0
	v_fmac_f32_e32 v67, v69, v67
	v_div_scale_f32 v69, vcc, v72, v73, v72
	v_mul_f32_e32 v71, v69, v67
	v_fma_f32 v74, -v65, v71, v69
	v_fmac_f32_e32 v71, v74, v67
	v_fma_f32 v65, -v65, v71, v69
	v_div_fmas_f32 v65, v65, v67, v71
	v_mov_b32_e32 v67, v64
	v_mov_b32_e32 v69, v70
	v_div_fixup_f32 v80, v65, v73, v72
	v_pk_mul_f32 v[64:65], v[66:67], v[68:69]
	v_cvt_pk_bf16_f32 v111, v16, v16
	v_sub_f32_e32 v64, v64, v65
	v_div_scale_f32 v65, s[42:43], v73, v73, v64
	v_rcp_f32_e32 v66, v65
	v_xor_b32_e32 v16, 0x80000000, v18
	v_xor_b32_e32 v20, 0x80000000, v20
	v_cvt_pk_bf16_f32 v112, v16, v16
	v_xor_b32_e32 v16, 0x80000000, v19
	v_mov_b32_e32 v119, v116
	v_cvt_pk_bf16_f32 v106, v20, v20
	v_xor_b32_e32 v20, 0x80000000, v21
	v_cvt_pk_bf16_f32 v113, v16, v16
	v_add_f32_e32 v16, -1.0, v156
	v_mov_b32_e32 v17, v114
	v_pk_mul_f32 v[18:19], v[116:117], v[118:119] op_sel_hi:[0,1]
	v_cvt_pk_bf16_f32 v107, v20, v20
	v_xor_b32_e32 v20, 0x80000000, v22
	v_pk_fma_f32 v[18:19], v[114:115], v[16:17], v[18:19] op_sel_hi:[0,1,1]
	v_fma_f32 v67, -v65, v66, 1.0
	v_cvt_pk_bf16_f32 v108, v20, v20
	v_xor_b32_e32 v20, 0x80000000, v23
	v_div_scale_f32 v17, s[42:43], v19, v19, v18
	v_fmac_f32_e32 v66, v67, v66
	v_div_scale_f32 v67, vcc, v64, v73, v64
	v_cvt_pk_bf16_f32 v109, v20, v20
	v_rcp_f32_e32 v20, v17
	v_mul_f32_e32 v68, v67, v66
	v_fma_f32 v69, -v65, v68, v67
	v_fmac_f32_e32 v68, v69, v66
	v_fma_f32 v65, -v65, v68, v67
	v_fma_f32 v21, -v17, v20, 1.0
	v_div_fmas_f32 v65, v65, v66, v68
	v_fmac_f32_e32 v20, v21, v20
	v_div_scale_f32 v21, vcc, v18, v19, v18
	v_mul_f32_e32 v22, v21, v20
	v_fma_f32 v23, -v17, v22, v21
	v_fmac_f32_e32 v22, v23, v20
	v_fma_f32 v17, -v17, v22, v21
	v_div_fmas_f32 v17, v17, v20, v22
	v_mov_b32_e32 v115, v116
	v_mov_b32_e32 v119, v16
	v_div_fixup_f32 v18, v17, v19, v18
	v_pk_mul_f32 v[16:17], v[114:115], v[118:119]
	s_ashr_i32 s44, s17, 8
	v_sub_f32_e32 v16, v16, v17
	v_div_scale_f32 v17, s[42:43], v19, v19, v16
	v_rcp_f32_e32 v20, v17
	s_ashr_i32 s45, s44, 31
	s_lshl_b64 s[42:43], s[44:45], 12
	s_lshl_b32 s22, s22, 8
	v_fma_f32 v21, -v17, v20, 1.0
	v_fmac_f32_e32 v20, v21, v20
	v_div_scale_f32 v21, vcc, v16, v19, v16
	v_mul_f32_e32 v22, v21, v20
	v_fma_f32 v23, -v17, v22, v21
	v_fmac_f32_e32 v22, v23, v20
	v_fma_f32 v17, -v17, v22, v21
	v_div_fmas_f32 v17, v17, v20, v22
	v_div_fixup_f32 v16, v17, v19, v16
	v_pk_mul_f32 v[20:21], v[12:13], v[16:17] op_sel_hi:[1,0]
	s_or_b32 s22, s42, s22
	v_pk_fma_f32 v[20:21], v[8:9], v[18:19], v[20:21] op_sel_hi:[1,0,1] neg_lo:[0,0,1] neg_hi:[0,0,1]
	v_readlane_b32 s24, v253, 21
	v_cvt_pk_bf16_f32 v114, v20, v21
	v_lshlrev_b32_e32 v22, 16, v114
	v_and_b32_e32 v23, 0xffff0000, v114
	v_pk_add_f32 v[20:21], v[20:21], v[22:23] neg_lo:[0,1] neg_hi:[0,1]
	v_readlane_b32 s25, v253, 22
	v_cvt_pk_bf16_f32 v118, v20, v21
	v_pk_mul_f32 v[20:21], v[14:15], v[16:17] op_sel_hi:[1,0]
	s_lshl_b32 s34, s6, 1
	v_pk_fma_f32 v[20:21], v[10:11], v[18:19], v[20:21] op_sel_hi:[1,0,1] neg_lo:[0,0,1] neg_hi:[0,0,1]
	v_div_fixup_f32 v82, v65, v73, v64
	v_cvt_pk_bf16_f32 v115, v20, v21
	v_lshlrev_b32_e32 v22, 16, v115
	v_and_b32_e32 v23, 0xffff0000, v115
	v_pk_add_f32 v[20:21], v[20:21], v[22:23] neg_lo:[0,1] neg_hi:[0,1]
	v_pk_mul_f32 v[64:65], v[60:61], v[82:83] op_sel_hi:[1,0]
	v_cvt_pk_bf16_f32 v119, v20, v21
	v_pk_mul_f32 v[20:21], v[4:5], v[16:17] op_sel_hi:[1,0]
	v_pk_fma_f32 v[66:67], v[56:57], v[80:81], v[64:65] op_sel_hi:[1,0,1] neg_lo:[0,0,1] neg_hi:[0,0,1]
	v_pk_fma_f32 v[20:21], v[0:1], v[18:19], v[20:21] op_sel_hi:[1,0,1] neg_lo:[0,0,1] neg_hi:[0,0,1]
	v_pk_mul_f32 v[0:1], v[0:1], v[16:17] op_sel_hi:[1,0]
	v_cvt_pk_bf16_f32 v116, v20, v21
	v_pk_fma_f32 v[0:1], v[4:5], v[18:19], v[0:1] op_sel_hi:[1,0,1]
	v_lshlrev_b32_e32 v22, 16, v116
	v_cvt_pk_bf16_f32 v124, v0, v1
	v_lshlrev_b32_e32 v4, 16, v124
	v_and_b32_e32 v5, 0xffff0000, v124
	v_pk_add_f32 v[0:1], v[0:1], v[4:5] neg_lo:[0,1] neg_hi:[0,1]
	v_and_b32_e32 v23, 0xffff0000, v116
	v_cvt_pk_bf16_f32 v128, v0, v1
	v_pk_mul_f32 v[0:1], v[2:3], v[16:17] op_sel_hi:[1,0]
	v_pk_add_f32 v[20:21], v[20:21], v[22:23] neg_lo:[0,1] neg_hi:[0,1]
	v_pk_fma_f32 v[0:1], v[6:7], v[18:19], v[0:1] op_sel_hi:[1,0,1]
	v_cvt_pk_bf16_f32 v120, v20, v21
	v_pk_mul_f32 v[20:21], v[6:7], v[16:17] op_sel_hi:[1,0]
	v_cvt_pk_bf16_f32 v125, v0, v1
	v_pk_fma_f32 v[20:21], v[2:3], v[18:19], v[20:21] op_sel_hi:[1,0,1] neg_lo:[0,0,1] neg_hi:[0,0,1]
	v_lshlrev_b32_e32 v2, 16, v125
	v_and_b32_e32 v3, 0xffff0000, v125
	v_pk_add_f32 v[0:1], v[0:1], v[2:3] neg_lo:[0,1] neg_hi:[0,1]
	v_cvt_pk_bf16_f32 v64, v66, v67
	v_cvt_pk_bf16_f32 v129, v0, v1
	v_mov_b32_e32 v1, s43
	v_or_b32_e32 v0, s22, v138
	v_lshlrev_b64 v[0:1], 10, v[0:1]
	v_lshl_add_u64 v[0:1], s[24:25], 0, v[0:1]
	v_lshl_add_u64 v[0:1], v[0:1], 0, s[34:35]
	v_lshl_add_u64 v[0:1], v[0:1], 0, v[96:97]
; __device__ __forceinline__ float bf_lo(unsigned w) { return __uint_as_float(w << 16); }
; __device__ __forceinline__ float bf_hi(unsigned w) { return __uint_as_float(w & 0xffff0000u); }
; __device__ __forceinline__ unsigned pk_bf16(float lo, float hi) { return pg8::cvt_pk_bf16(lo, hi); }
; __device__ __forceinline__ void split_bf16x8(const float (&v)[8], bf16x8& hi8, bf16x8& lo8) {
;     u32x4 hw, lw;
; #pragma unroll
;     for (int k = 0; k < 4; ++k) { const unsigned h = pk_bf16(v[2 * k], v[2 * k + 1]); const unsigned lo = pk_bf16(v[2 * k] - bf_lo(h), v[2 * k + 1] - bf_hi(h)); hw[k] = h; lw[k] = lo; }
;     hi8 = __builtin_bit_cast(bf16x8, hw); lo8 = __builtin_bit_cast(bf16x8, lw);
; template <bool PASS2> __device__ __forceinline__ void ssm2_pass(const Ctx& c, int l) {
;     ...
;             for (int s_ = 0; s_ < 8; ++s_) { const float* src = (s_ < 4 ? c.inp(IN_CRE) : c.inp(IN_CIM)) + cb + 16 * (s_ & 3) + kq; const float sg = (s_ < 4) ? 1.f : -1.f;
;                 const f32x4 v0 = *(const f32x4*)src;
;                 const u32x4 w = {pk_bf16(sg * v0[0], sg * v0[0]), pk_bf16(sg * v0[1], sg * v0[1]), pk_bf16(sg * v0[2], sg * v0[2]), pk_bf16(sg * v0[3], sg * v0[3])};
;                 Cb[s_] = __builtin_bit_cast(bf16x8, w); }
;             dsk = c.inp(IN_DSKIP)[l * 256 + g * 16 + h]; }
;         float xAr = 0.f, xAi = 0.f, xBr = 0.f, xBi = 0.f;
;         if (PASS2 && tk > 0) {
;             float pAr = arA, pAi = aiA, pBr = arB, pBi = aiB;
; #pragma unroll
;             for (int k = 0; k < 8; ++k) { float nr = pAr * pAr - pAi * pAi, ni = 2.f * pAr * pAi; pAr = nr; pAi = ni; nr = pBr * pBr - pBi * pBi; ni = 2.f * pBr * pBi; pBr = nr; pBi = ni; }
;             for (int j = 0; j < tk; ++j) { const float2 eA = *(const float2*)(send + ((size_t)(bg * 16 + j) * 64 + q) * 2), eB = *(const float2*)(send + ((size_t)(bg * 16 + j) * 64 + 32 + q) * 2);
;                 float nr = pAr * xAr - pAi * xAi + eA.x, ni = pAr * xAi + pAi * xAr + eA.y; xAr = nr; xAi = ni;
;                 nr = pBr * xBr - pBi * xBi + eB.x; ni = pBr * xBi + pBi * xBr + eB.y; xBr = nr; xBi = ni; }
;         }
;         const size_t row0 = (size_t)b * SEQ + tk * 256;
;         const bf16_t* up = ZC + (row0 + q) * 512 + g * 16 + 8 * hi;
;         bf16x8 an = *(const bf16x8*)up;
	global_load_dwordx4 v[134:137], v[0:1], off nt
	v_lshlrev_b32_e32 v68, 16, v64
	v_and_b32_e32 v69, 0xffff0000, v64
	v_pk_add_f32 v[66:67], v[66:67], v[68:69] neg_lo:[0,1] neg_hi:[0,1]
	v_pk_mul_f32 v[56:57], v[56:57], v[82:83] op_sel_hi:[1,0]
	v_cvt_pk_bf16_f32 v68, v66, v67
	v_pk_mul_f32 v[66:67], v[62:63], v[82:83] op_sel_hi:[1,0]
	v_pk_mul_f32 v[8:9], v[8:9], v[16:17] op_sel_hi:[1,0]
	v_pk_fma_f32 v[66:67], v[58:59], v[80:81], v[66:67] op_sel_hi:[1,0,1] neg_lo:[0,0,1] neg_hi:[0,0,1]
	v_pk_fma_f32 v[56:57], v[60:61], v[80:81], v[56:57] op_sel_hi:[1,0,1]
	v_cvt_pk_bf16_f32 v65, v66, v67
	v_lshlrev_b32_e32 v70, 16, v65
	v_and_b32_e32 v71, 0xffff0000, v65
	v_pk_add_f32 v[66:67], v[66:67], v[70:71] neg_lo:[0,1] neg_hi:[0,1]
	v_pk_fma_f32 v[8:9], v[12:13], v[18:19], v[8:9] op_sel_hi:[1,0,1]
	v_cvt_pk_bf16_f32 v69, v66, v67
	v_pk_mul_f32 v[66:67], v[52:53], v[82:83] op_sel_hi:[1,0]
	v_cvt_pk_bf16_f32 v122, v8, v9
	v_pk_fma_f32 v[70:71], v[48:49], v[80:81], v[66:67] op_sel_hi:[1,0,1] neg_lo:[0,0,1] neg_hi:[0,0,1]
	v_pk_mul_f32 v[48:49], v[48:49], v[82:83] op_sel_hi:[1,0]
	v_cvt_pk_bf16_f32 v66, v70, v71
	v_lshlrev_b32_e32 v72, 16, v66
	v_and_b32_e32 v73, 0xffff0000, v66
	v_pk_add_f32 v[70:71], v[70:71], v[72:73] neg_lo:[0,1] neg_hi:[0,1]
	v_pk_mul_f32 v[72:73], v[54:55], v[82:83] op_sel_hi:[1,0]
	v_pk_fma_f32 v[48:49], v[52:53], v[80:81], v[48:49] op_sel_hi:[1,0,1]
	v_pk_fma_f32 v[72:73], v[50:51], v[80:81], v[72:73] op_sel_hi:[1,0,1] neg_lo:[0,0,1] neg_hi:[0,0,1]
	v_cvt_pk_bf16_f32 v70, v70, v71
	v_cvt_pk_bf16_f32 v67, v72, v73
	v_lshlrev_b32_e32 v74, 16, v67
	v_and_b32_e32 v75, 0xffff0000, v67
	v_pk_add_f32 v[72:73], v[72:73], v[74:75] neg_lo:[0,1] neg_hi:[0,1]
	v_cvt_pk_bf16_f32 v74, v48, v49
	v_cvt_pk_bf16_f32 v71, v72, v73
	v_cvt_pk_bf16_f32 v72, v56, v57
	v_lshlrev_b32_e32 v60, 16, v72
	v_and_b32_e32 v61, 0xffff0000, v72
	v_lshlrev_b32_e32 v52, 16, v74
	v_and_b32_e32 v53, 0xffff0000, v74
	v_lshlrev_b32_e32 v12, 16, v122
	v_and_b32_e32 v13, 0xffff0000, v122
	v_pk_add_f32 v[56:57], v[56:57], v[60:61] neg_lo:[0,1] neg_hi:[0,1]
	v_pk_add_f32 v[48:49], v[48:49], v[52:53] neg_lo:[0,1] neg_hi:[0,1]
	v_pk_add_f32 v[8:9], v[8:9], v[12:13] neg_lo:[0,1] neg_hi:[0,1]
	v_cvt_pk_bf16_f32 v76, v56, v57
	v_pk_mul_f32 v[56:57], v[58:59], v[82:83] op_sel_hi:[1,0]
	v_cvt_pk_bf16_f32 v78, v48, v49
	v_pk_mul_f32 v[48:49], v[50:51], v[82:83] op_sel_hi:[1,0]
	v_cvt_pk_bf16_f32 v126, v8, v9
	v_pk_mul_f32 v[8:9], v[10:11], v[16:17] op_sel_hi:[1,0]
	v_pk_fma_f32 v[56:57], v[62:63], v[80:81], v[56:57] op_sel_hi:[1,0,1]
	v_pk_fma_f32 v[48:49], v[54:55], v[80:81], v[48:49] op_sel_hi:[1,0,1]
	v_xor_b32_e32 v28, 0x80000000, v28
	v_xor_b32_e32 v24, 0x80000000, v24
	v_pk_fma_f32 v[8:9], v[14:15], v[18:19], v[8:9] op_sel_hi:[1,0,1]
	s_and_b32 s36, s21, 15
	v_or_b32_e32 v0, s42, v138
	v_cvt_pk_bf16_f32 v73, v56, v57
	v_cvt_pk_bf16_f32 v75, v48, v49
	v_cvt_pk_bf16_f32 v98, v28, v28
	v_xor_b32_e32 v28, 0x80000000, v29
	v_cvt_pk_bf16_f32 v102, v24, v24
	v_xor_b32_e32 v24, 0x80000000, v25
	v_cvt_pk_bf16_f32 v117, v20, v21
	v_cvt_pk_bf16_f32 v123, v8, v9
	s_lshl_b32 s46, s36, 17
	s_and_b32 s31, s31, 15
	s_lshl_b64 s[44:45], s[44:45], 21
	v_mov_b32_e32 v1, s43
	v_lshl_or_b32 v0, s36, 8, v0
	v_lshlrev_b32_e32 v58, 16, v73
	v_and_b32_e32 v59, 0xffff0000, v73
	v_lshlrev_b32_e32 v50, 16, v75
	v_and_b32_e32 v51, 0xffff0000, v75
	v_cvt_pk_bf16_f32 v99, v28, v28
	v_xor_b32_e32 v28, 0x80000000, v30
	v_cvt_pk_bf16_f32 v103, v24, v24
	v_xor_b32_e32 v24, 0x80000000, v26
	v_lshlrev_b32_e32 v22, 16, v117
	v_and_b32_e32 v23, 0xffff0000, v117
	v_lshlrev_b32_e32 v10, 16, v123
	v_and_b32_e32 v11, 0xffff0000, v123
	s_lshl_b32 s31, s31, 5
	s_or_b32 s6, s44, s46
	v_lshlrev_b64 v[0:1], 10, v[0:1]
	v_pk_add_f32 v[56:57], v[56:57], v[58:59] neg_lo:[0,1] neg_hi:[0,1]
	v_pk_add_f32 v[48:49], v[48:49], v[50:51] neg_lo:[0,1] neg_hi:[0,1]
	v_cvt_pk_bf16_f32 v100, v28, v28
	v_xor_b32_e32 v28, 0x80000000, v31
	v_cvt_pk_bf16_f32 v104, v24, v24
	v_xor_b32_e32 v24, 0x80000000, v27
	v_pk_add_f32 v[20:21], v[20:21], v[22:23] neg_lo:[0,1] neg_hi:[0,1]
	v_pk_add_f32 v[8:9], v[8:9], v[10:11] neg_lo:[0,1] neg_hi:[0,1]
	s_or_b32 s44, s6, s31
	v_or_b32_e32 v0, s31, v0
	s_waitcnt vmcnt(0)
	v_mov_b64_e32 v[130:131], v[134:135]
	v_cvt_pk_bf16_f32 v77, v56, v57
	v_cvt_pk_bf16_f32 v79, v48, v49
	v_cvt_pk_bf16_f32 v80, v44, v44
	v_cvt_pk_bf16_f32 v81, v45, v45
	v_cvt_pk_bf16_f32 v82, v46, v46
	v_cvt_pk_bf16_f32 v83, v47, v47
	v_cvt_pk_bf16_f32 v84, v40, v40
	v_cvt_pk_bf16_f32 v85, v41, v41
	v_cvt_pk_bf16_f32 v86, v42, v42
	v_cvt_pk_bf16_f32 v87, v43, v43
	v_cvt_pk_bf16_f32 v88, v36, v36
	v_cvt_pk_bf16_f32 v89, v37, v37
	v_cvt_pk_bf16_f32 v90, v38, v38
	v_cvt_pk_bf16_f32 v91, v39, v39
	v_cvt_pk_bf16_f32 v92, v32, v32
	v_cvt_pk_bf16_f32 v93, v33, v33
	v_cvt_pk_bf16_f32 v94, v34, v34
	v_cvt_pk_bf16_f32 v95, v35, v35
	v_cvt_pk_bf16_f32 v101, v28, v28
	v_cvt_pk_bf16_f32 v105, v24, v24
	v_cvt_pk_bf16_f32 v121, v20, v21
	v_cvt_pk_bf16_f32 v127, v8, v9
	v_lshl_add_u64 v[160:161], v[150:151], 0, s[44:45]
	v_lshl_add_u64 v[162:163], v[152:153], 0, v[0:1]
	v_lshl_add_u64 v[164:165], v[154:155], 0, s[44:45]
	s_mov_b64 s[42:43], 0
	v_mov_b64_e32 v[132:133], v[136:137]
	s_branch .LBB0_125

; __device__ __forceinline__ void ssm2_coef(const Ctx& c, int l, int g, int p, int hi, float& ar, float& ai, float (&br)[8], float (&bi)[8]) {
;     const int gp = (l * 16 + g) * 64 + p;
;     const float are = c.inp(IN_ARE)[gp], aim = c.inp(IN_AIM)[gp], dt = expf(c.inp(IN_LOGDT)[l * 16 + g]);
;     const float mag = expf(are * dt), ang = aim * dt;
;     ar = mag * cosf(ang); ai = mag * sinf(ang);
;     const float den = are * are + aim * aim, nr = ar - 1.0f;
;     const float cr = (nr * are + ai * aim) / den, ci = (ai * are - nr * aim) / den;
;     const f32x4* pr = (const f32x4*)(c.inp(IN_BRE) + (size_t)gp * 16 + 8 * hi); const f32x4* pi = (const f32x4*)(c.inp(IN_BIM) + (size_t)gp * 16 + 8 * hi);
; #pragma unroll
;     for (int q4 = 0; q4 < 2; ++q4) { const f32x4 r4 = pr[q4], i4 = pi[q4];
.LBB0_371:
	s_or_b64 exec, exec, s[40:41]
	s_load_dwordx4 s[48:51], s[52:53], 0x40
	v_lshlrev_b64 v[2:3], 6, v[16:17]
	v_lshlrev_b32_e32 v96, 2, v108
	global_load_dword v18, v[0:1], off offset:128
	s_brev_b32 s16, 18
	s_waitcnt lgkmcnt(0)
	v_lshl_add_u64 v[0:1], s[48:49], 0, v[2:3]
	v_lshl_add_u64 v[2:3], s[50:51], 0, v[2:3]
	v_lshl_add_u64 v[4:5], v[0:1], 0, v[96:97]
	v_lshl_add_u64 v[12:13], v[2:3], 0, v[96:97]
	global_load_dwordx4 v[0:3], v[4:5], off offset:16 nt
	global_load_dwordx4 v[8:11], v[4:5], off nt
	s_nop 0
	global_load_dwordx4 v[4:7], v[12:13], off offset:16 nt
	s_nop 0
	global_load_dwordx4 v[12:15], v[12:13], off nt
	s_nop 0
	global_load_dword v20, v[20:21], off offset:128
	s_waitcnt vmcnt(5)
	v_mul_f32_e32 v17, v26, v18
	v_and_b32_e32 v19, 0x7fffffff, v17
	v_lshrrev_b32_e32 v21, 23, v19
	v_and_b32_e32 v27, 0x7fffff, v19
	v_cmp_nlt_f32_e64 s[54:55], |v17|, s16
	v_add_u32_e32 v35, 0xffffff88, v21
	v_or_b32_e32 v30, 0x800000, v27
	s_and_saveexec_b64 s[16:17], s[54:55]
	s_xor_b64 s[60:61], exec, s[16:17]
	s_cbranch_execz .LBB0_373
	s_mov_b32 s16, 0xfe5163ab
	v_mad_u64_u32 v[36:37], s[16:17], v30, s16, 0
	v_mov_b32_e32 v38, v37
	v_mov_b32_e32 v39, v97
	s_mov_b32 s16, 0x3c439041
	v_mad_u64_u32 v[38:39], s[16:17], v30, s16, v[38:39]
	v_mov_b32_e32 v40, v39
	v_mov_b32_e32 v41, v97
	s_mov_b32 s16, 0xdb629599
	v_mad_u64_u32 v[40:41], s[16:17], v30, s16, v[40:41]
	v_cmp_lt_u32_e32 vcc, 63, v35
	v_mov_b32_e32 v42, v41
	v_mov_b32_e32 v43, v97
	s_mov_b32 s16, 0xf534ddc0
	v_cndmask_b32_e32 v21, 0, v224, vcc
	v_mad_u64_u32 v[42:43], s[16:17], v30, s16, v[42:43]
	v_add_u32_e32 v21, v21, v35
	v_mov_b32_e32 v44, v43
	v_mov_b32_e32 v45, v97
	s_mov_b32 s16, 0xfc2757d1
	v_cmp_lt_u32_e64 s[40:41], 31, v21
	v_mad_u64_u32 v[44:45], s[16:17], v30, s16, v[44:45]
	s_nop 0
	v_cndmask_b32_e64 v27, 0, v225, s[40:41]
	v_mov_b32_e32 v46, v45
	v_mov_b32_e32 v47, v97
	s_mov_b32 s16, 0x4e441529
	v_add_u32_e32 v21, v27, v21
	v_mad_u64_u32 v[46:47], s[16:17], v30, s16, v[46:47]
	v_cmp_lt_u32_e64 s[42:43], 31, v21
	v_mov_b32_e32 v48, v47
	v_mov_b32_e32 v49, v97
	s_mov_b32 s16, 0xa2f9836e
	v_cndmask_b32_e64 v27, 0, v225, s[42:43]
	v_mad_u64_u32 v[48:49], s[16:17], v30, s16, v[48:49]
	v_add_u32_e32 v21, v27, v21
	v_cndmask_b32_e32 v27, v46, v42, vcc
	v_cndmask_b32_e32 v33, v48, v44, vcc
	v_cndmask_b32_e32 v37, v49, v46, vcc
	v_cndmask_b32_e64 v34, v33, v27, s[40:41]
	v_cndmask_b32_e64 v33, v37, v33, s[40:41]
	v_cndmask_b32_e32 v37, v44, v40, vcc
	v_cndmask_b32_e64 v27, v27, v37, s[40:41]
	v_cndmask_b32_e64 v33, v33, v34, s[42:43]
	v_cndmask_b32_e64 v34, v34, v27, s[42:43]
	v_sub_u32_e32 v39, 32, v21
	v_alignbit_b32 v41, v33, v34, v39
	v_cmp_eq_u32_e64 s[44:45], 0, v21
	v_cndmask_b32_e32 v36, v40, v36, vcc
	s_mov_b32 s16, 0x3fc90fda
	v_cndmask_b32_e64 v21, v41, v33, s[44:45]
	v_cndmask_b32_e32 v33, v42, v38, vcc
	v_cndmask_b32_e64 v37, v37, v33, s[40:41]
	v_cndmask_b32_e64 v27, v27, v37, s[42:43]
	v_alignbit_b32 v38, v34, v27, v39
	v_cndmask_b32_e64 v34, v38, v34, s[44:45]
	v_bfe_u32 v42, v21, 29, 1
	v_cndmask_b32_e64 v33, v33, v36, s[40:41]
	v_alignbit_b32 v38, v21, v34, 30
	v_sub_u32_e32 v43, 0, v42
	v_cndmask_b32_e64 v33, v37, v33, s[42:43]
	v_xor_b32_e32 v38, v38, v43
	v_alignbit_b32 v36, v27, v33, v39
	v_cndmask_b32_e64 v27, v36, v27, s[44:45]
	v_ffbh_u32_e32 v36, v38
	v_alignbit_b32 v34, v34, v27, 30
	v_min_u32_e32 v36, 32, v36
	v_alignbit_b32 v27, v27, v33, 30
	v_xor_b32_e32 v34, v34, v43
	v_sub_u32_e32 v37, 31, v36
	v_xor_b32_e32 v27, v27, v43
	v_alignbit_b32 v38, v38, v34, v37
	v_alignbit_b32 v27, v34, v27, v37
	v_alignbit_b32 v33, v38, v27, 9
	v_ffbh_u32_e32 v34, v33
	v_min_u32_e32 v34, 32, v34
	v_lshrrev_b32_e32 v41, 29, v21
	v_not_b32_e32 v37, v34
	v_alignbit_b32 v27, v33, v27, v37
	v_lshlrev_b32_e32 v33, 31, v41
	v_or_b32_e32 v37, 0x33000000, v33
	v_add_lshl_u32 v34, v34, v36, 23
	v_lshrrev_b32_e32 v27, 9, v27
	v_sub_u32_e32 v34, v37, v34
	v_or_b32_e32 v33, 0.5, v33
	v_lshlrev_b32_e32 v36, 23, v36
	v_or_b32_e32 v27, v34, v27
	v_lshrrev_b32_e32 v34, 9, v38
	v_sub_u32_e32 v33, v33, v36
	v_or_b32_e32 v33, v34, v33
	v_mul_f32_e32 v34, 0x3fc90fda, v33
	v_fma_f32 v36, v33, s16, -v34
	v_fmac_f32_e32 v36, 0x33a22168, v33
	v_fmac_f32_e32 v36, 0x3fc90fda, v27
	v_lshrrev_b32_e32 v21, 30, v21
	v_add_f32_e32 v34, v34, v36
	v_add_u32_e32 v33, v42, v21

; __device__ __forceinline__ float bf_lo(unsigned w) { return __uint_as_float(w << 16); }
; __device__ __forceinline__ float bf_hi(unsigned w) { return __uint_as_float(w & 0xffff0000u); }
; __device__ __forceinline__ unsigned pk_bf16(float lo, float hi) { return pg8::cvt_pk_bf16(lo, hi); }
; __device__ __forceinline__ void ssm2_coef(const Ctx& c, int l, int g, int p, int hi, float& ar, float& ai, float (&br)[8], float (&bi)[8]) {
;     ...
;     const float are = c.inp(IN_ARE)[gp], aim = c.inp(IN_AIM)[gp], dt = expf(c.inp(IN_LOGDT)[l * 16 + g]);
;     const float mag = expf(are * dt), ang = aim * dt;
;     ar = mag * cosf(ang); ai = mag * sinf(ang);
;     const float den = are * are + aim * aim, nr = ar - 1.0f;
;     const float cr = (nr * are + ai * aim) / den, ci = (ai * are - nr * aim) / den;
;     const f32x4* pr = (const f32x4*)(c.inp(IN_BRE) + (size_t)gp * 16 + 8 * hi); const f32x4* pi = (const f32x4*)(c.inp(IN_BIM) + (size_t)gp * 16 + 8 * hi);
; #pragma unroll
;     for (int q4 = 0; q4 < 2; ++q4) { const f32x4 r4 = pr[q4], i4 = pi[q4];
; #pragma unroll
;         for (int i = 0; i < 4; ++i) { br[4 * q4 + i] = cr * r4[i] - ci * i4[i]; bi[4 * q4 + i] = cr * i4[i] + ci * r4[i]; } }
; }
; __device__ __forceinline__ void split_bf16x8(const float (&v)[8], bf16x8& hi8, bf16x8& lo8) {
;     u32x4 hw, lw;
; #pragma unroll
;     for (int k = 0; k < 4; ++k) { const unsigned h = pk_bf16(v[2 * k], v[2 * k + 1]); const unsigned lo = pk_bf16(v[2 * k] - bf_lo(h), v[2 * k + 1] - bf_hi(h)); hw[k] = h; lw[k] = lo; }
;     hi8 = __builtin_bit_cast(bf16x8, hw); lo8 = __builtin_bit_cast(bf16x8, lw);
.LBB0_379:
	s_or_b64 exec, exec, s[40:41]
	s_waitcnt vmcnt(0)
	v_mul_f32_e32 v30, v26, v20
	v_mul_f32_e32 v35, 0x3fb8aa3b, v30
	s_mov_b32 s16, 0x3fb8aa3b
	v_fma_f32 v36, v30, s16, -v35
	v_rndne_f32_e32 v37, v35
	v_fmac_f32_e32 v36, 0x32a5705f, v30
	v_sub_f32_e32 v35, v35, v37
	v_add_f32_e32 v35, v35, v36
	v_cvt_i32_f32_e32 v36, v37
	v_exp_f32_e32 v35, v35
	s_mov_b32 s17, 0xc2ce8ed0
	v_cmp_ngt_f32_e32 vcc, s17, v30
	s_mov_b32 s20, 0x42b17218
	v_ldexp_f32 v35, v35, v36
	v_cndmask_b32_e32 v35, 0, v35, vcc
	v_cmp_nlt_f32_e32 vcc, s20, v30
	v_mul_f32_e32 v26, v22, v26
	v_mul_f32_e32 v37, 0x3fb8aa3b, v26
	v_cndmask_b32_e32 v30, v223, v35, vcc
	v_mul_f32_e32 v35, v34, v34
	v_fmamk_f32 v36, v35, 0xb94c1982, v215
	v_fmaak_f32 v36, v35, v36, 0xbe2aaa9d
	v_mul_f32_e32 v36, v35, v36
	v_fma_f32 v38, v26, s16, -v37
	v_rndne_f32_e32 v39, v37
	v_fmac_f32_e32 v34, v34, v36
	v_fmamk_f32 v36, v35, 0x37d75334, v216
	v_fmac_f32_e32 v38, 0x32a5705f, v26
	v_sub_f32_e32 v37, v37, v39
	v_fmaak_f32 v36, v35, v36, 0x3d2aabf7
	v_add_f32_e32 v37, v37, v38
	v_fmaak_f32 v36, v35, v36, 0xbf000004
	v_exp_f32_e32 v37, v37
	v_cvt_i32_f32_e32 v38, v39
	v_fma_f32 v35, v35, v36, 1.0
	v_and_b32_e32 v36, 1, v33
	v_cmp_eq_u32_e32 vcc, 0, v36
	v_lshlrev_b32_e32 v33, 30, v33
	s_brev_b32 s16, 1
	v_cndmask_b32_e64 v34, -v34, v35, vcc
	v_bitop3_b32 v34, v33, v34, s16 bitop3:0x6c
	v_ldexp_f32 v33, v37, v38
	v_cmp_ngt_f32_e32 vcc, s17, v26
	v_mov_b32_e32 v115, v24
	v_mov_b32_e32 v119, v18
	v_cndmask_b32_e32 v33, 0, v33, vcc
	v_cmp_nlt_f32_e32 vcc, s20, v26
	s_movk_i32 s20, 0x1f8
	s_ashr_i32 s42, s46, 8
	v_cndmask_b32_e32 v26, v223, v33, vcc
	v_mul_f32_e32 v33, v29, v29
	v_fmamk_f32 v35, v33, 0xb94c1982, v215
	v_fmaak_f32 v35, v33, v35, 0xbe2aaa9d
	v_mul_f32_e32 v35, v33, v35
	v_fmac_f32_e32 v29, v29, v35
	v_fmamk_f32 v35, v33, 0x37d75334, v216
	v_fmaak_f32 v35, v33, v35, 0x3d2aabf7
	v_fmaak_f32 v35, v33, v35, 0xbf000004
	v_fma_f32 v33, v33, v35, 1.0
	v_and_b32_e32 v35, 1, v28
	v_cmp_eq_u32_e32 vcc, 0, v35
	v_lshlrev_b32_e32 v28, 30, v28
	s_ashr_i32 s43, s42, 31
	v_cndmask_b32_e64 v29, -v29, v33, vcc
	v_bitop3_b32 v28, v28, v29, s16 bitop3:0x6c
	v_cmp_class_f32_e64 vcc, v23, s20
	v_xor_b32_e32 v23, v25, v23
	s_lshl_b32 s12, s12, 8
	v_cndmask_b32_e32 v35, v226, v28, vcc
	v_mul_f32_e32 v28, v32, v32
	v_fmamk_f32 v29, v28, 0xb94c1982, v215
	v_fmaak_f32 v29, v28, v29, 0xbe2aaa9d
	v_mul_f32_e32 v29, v28, v29
	v_fmac_f32_e32 v32, v32, v29
	v_fmamk_f32 v29, v28, 0x37d75334, v216
	v_fmaak_f32 v29, v28, v29, 0x3d2aabf7
	v_fmaak_f32 v29, v28, v29, 0xbf000004
	v_fma_f32 v28, v28, v29, 1.0
	v_and_b32_e32 v29, 1, v31
	v_cmp_eq_u32_e64 s[40:41], 0, v29
	v_lshlrev_b32_e32 v29, 30, v31
	v_and_b32_e32 v29, 0x80000000, v29
	v_cndmask_b32_e64 v28, v28, v32, s[40:41]
	v_xor_b32_e32 v23, v23, v29
	v_xor_b32_e32 v23, v23, v28
	v_cndmask_b32_e32 v23, v226, v23, vcc
	v_mul_f32_e32 v114, v26, v23
	v_fma_f32 v28, v26, v35, -1.0
	v_mov_b32_e32 v29, v22
	v_pk_mul_f32 v[32:33], v[24:25], v[114:115] op_sel_hi:[0,1]
	v_pk_fma_f32 v[32:33], v[22:23], v[28:29], v[32:33] op_sel_hi:[0,1,1]
	v_div_scale_f32 v23, s[16:17], v33, v33, v32
	v_rcp_f32_e32 v25, v23
	v_mul_f32_e32 v124, v26, v35
	v_cmp_class_f32_e64 s[40:41], v17, s20
	v_mov_b32_e32 v115, v28
	v_fma_f32 v26, -v23, v25, 1.0
	v_fmac_f32_e32 v25, v26, v25
	v_div_scale_f32 v26, vcc, v32, v33, v32
	v_mul_f32_e32 v29, v26, v25
	v_cndmask_b32_e64 v31, v226, v34, s[40:41]
	v_fma_f32 v34, -v23, v29, v26
	v_fmac_f32_e32 v29, v34, v25
	v_fma_f32 v26, -v23, v29, v26
	v_mov_b32_e32 v23, v24
	v_pk_mul_f32 v[22:23], v[22:23], v[114:115]
	v_xor_b32_e32 v17, v19, v17
	v_sub_f32_e32 v23, v22, v23
	v_div_scale_f32 v24, s[16:17], v33, v33, v23
	v_rcp_f32_e32 v28, v24
	v_div_fmas_f32 v22, v26, v25, v29
	v_div_fixup_f32 v22, v22, v33, v32
	s_and_b32 s20, s6, 15
	v_fma_f32 v25, -v24, v28, 1.0
	v_fmac_f32_e32 v28, v25, v28
	v_div_scale_f32 v25, vcc, v23, v33, v23
	v_mul_f32_e32 v26, v25, v28
	v_fma_f32 v29, -v24, v26, v25
	v_fmac_f32_e32 v26, v29, v28
	v_fma_f32 v24, -v24, v26, v25
	v_div_fmas_f32 v24, v24, v28, v26
	v_div_fixup_f32 v24, v24, v33, v23
	v_pk_mul_f32 v[28:29], v[12:13], v[24:25] op_sel_hi:[1,0]
	s_lshl_b32 s34, s13, 5
	v_pk_fma_f32 v[28:29], v[8:9], v[22:23], v[28:29] op_sel_hi:[1,0,1] neg_lo:[0,0,1] neg_hi:[0,0,1]
	v_pk_mul_f32 v[8:9], v[8:9], v[24:25] op_sel_hi:[1,0]
	v_cvt_pk_bf16_f32 v64, v28, v29
	v_lshlrev_b32_e32 v32, 16, v64
	v_and_b32_e32 v33, 0xffff0000, v64
	v_pk_add_f32 v[28:29], v[28:29], v[32:33] neg_lo:[0,1] neg_hi:[0,1]
	v_pk_fma_f32 v[8:9], v[12:13], v[22:23], v[8:9] op_sel_hi:[1,0,1]
	v_cvt_pk_bf16_f32 v68, v28, v29
	v_pk_mul_f32 v[28:29], v[14:15], v[24:25] op_sel_hi:[1,0]
	v_cvt_pk_bf16_f32 v72, v8, v9
	v_pk_fma_f32 v[28:29], v[10:11], v[22:23], v[28:29] op_sel_hi:[1,0,1] neg_lo:[0,0,1] neg_hi:[0,0,1]
	v_lshlrev_b32_e32 v12, 16, v72
	v_cvt_pk_bf16_f32 v65, v28, v29
	v_lshlrev_b32_e32 v32, 16, v65
	v_and_b32_e32 v33, 0xffff0000, v65
	v_pk_add_f32 v[28:29], v[28:29], v[32:33] neg_lo:[0,1] neg_hi:[0,1]
	v_and_b32_e32 v13, 0xffff0000, v72
	v_cvt_pk_bf16_f32 v69, v28, v29
	v_pk_mul_f32 v[28:29], v[4:5], v[24:25] op_sel_hi:[1,0]
	v_pk_add_f32 v[8:9], v[8:9], v[12:13] neg_lo:[0,1] neg_hi:[0,1]
	v_pk_fma_f32 v[28:29], v[0:1], v[22:23], v[28:29] op_sel_hi:[1,0,1] neg_lo:[0,0,1] neg_hi:[0,0,1]
	v_pk_mul_f32 v[0:1], v[0:1], v[24:25] op_sel_hi:[1,0]
	v_cvt_pk_bf16_f32 v66, v28, v29
	v_pk_fma_f32 v[0:1], v[4:5], v[22:23], v[0:1] op_sel_hi:[1,0,1]
	v_lshlrev_b32_e32 v32, 16, v66
	v_cvt_pk_bf16_f32 v74, v0, v1
	v_and_b32_e32 v33, 0xffff0000, v66
	v_lshlrev_b32_e32 v4, 16, v74
	v_and_b32_e32 v5, 0xffff0000, v74
	v_pk_add_f32 v[28:29], v[28:29], v[32:33] neg_lo:[0,1] neg_hi:[0,1]
; __device__ __forceinline__ void ssm2_coef(const Ctx& c, int l, int g, int p, int hi, float& ar, float& ai, float (&br)[8], float (&bi)[8]) {
;     const int gp = (l * 16 + g) * 64 + p;
;     const float are = c.inp(IN_ARE)[gp], aim = c.inp(IN_AIM)[gp], dt = expf(c.inp(IN_LOGDT)[l * 16 + g]);
;     const float mag = expf(are * dt), ang = aim * dt;
;     ar = mag * cosf(ang); ai = mag * sinf(ang);
;     const float den = are * are + aim * aim, nr = ar - 1.0f;
;     const float cr = (nr * are + ai * aim) / den, ci = (ai * are - nr * aim) / den;
;     const f32x4* pr = (const f32x4*)(c.inp(IN_BRE) + (size_t)gp * 16 + 8 * hi); const f32x4* pi = (const f32x4*)(c.inp(IN_BIM) + (size_t)gp * 16 + 8 * hi);
; #pragma unroll
;     for (int q4 = 0; q4 < 2; ++q4) { const f32x4 r4 = pr[q4], i4 = pi[q4];
; #pragma unroll
;         for (int i = 0; i < 4; ++i) { br[4 * q4 + i] = cr * r4[i] - ci * i4[i]; bi[4 * q4 + i] = cr * i4[i] + ci * r4[i]; } }
; }
; __device__ __forceinline__ void split_bf16x8(const float (&v)[8], bf16x8& hi8, bf16x8& lo8) {
;     u32x4 hw, lw;
; #pragma unroll
;     for (int k = 0; k < 4; ++k) { const unsigned h = pk_bf16(v[2 * k], v[2 * k + 1]); const unsigned lo = pk_bf16(v[2 * k] - bf_lo(h), v[2 * k + 1] - bf_hi(h)); hw[k] = h; lw[k] = lo; }
;     hi8 = __builtin_bit_cast(bf16x8, hw); lo8 = __builtin_bit_cast(bf16x8, lw);
; }
; template <bool PASS2> __device__ __forceinline__ void ssm2_pass(const Ctx& c, int l) {
;     ...
;         { float t0[8], t1[8];
;           ssm2_coef(c, l, g, q, hi, arA, aiA, t0, t1); split_bf16x8(t0, Bh[0], Bl[0]); split_bf16x8(t1, Bh[2], Bl[2]);
;           ssm2_coef(c, l, g, 32 + q, hi, arB, aiB, t0, t1); split_bf16x8(t0, Bh[1], Bl[1]); split_bf16x8(t1, Bh[3], Bl[3]); }
;         bf16x8 Cb[8]; float dsk = 0.f;
;         if (PASS2) { const int h = lane & 15, kq = 4 * (lane >> 4); const size_t cb = ((size_t)(l * 16 + g) * 16 + h) * 64;
; #pragma unroll
;             for (int s_ = 0; s_ < 8; ++s_) { const float* src = (s_ < 4 ? c.inp(IN_CRE) : c.inp(IN_CIM)) + cb + 16 * (s_ & 3) + kq; const float sg = (s_ < 4) ? 1.f : -1.f;
;                 const f32x4 v0 = *(const f32x4*)src;
;                 const u32x4 w = {pk_bf16(sg * v0[0], sg * v0[0]), pk_bf16(sg * v0[1], sg * v0[1]), pk_bf16(sg * v0[2], sg * v0[2]), pk_bf16(sg * v0[3], sg * v0[3])};
;                 Cb[s_] = __builtin_bit_cast(bf16x8, w); }
	v_pk_add_f32 v[0:1], v[0:1], v[4:5] neg_lo:[0,1] neg_hi:[0,1]
	v_cvt_pk_bf16_f32 v70, v28, v29
	v_pk_mul_f32 v[28:29], v[6:7], v[24:25] op_sel_hi:[1,0]
	v_cvt_pk_bf16_f32 v76, v8, v9
	v_pk_mul_f32 v[8:9], v[10:11], v[24:25] op_sel_hi:[1,0]
	v_cvt_pk_bf16_f32 v78, v0, v1
	v_pk_mul_f32 v[0:1], v[2:3], v[24:25] op_sel_hi:[1,0]
	v_pk_fma_f32 v[28:29], v[2:3], v[22:23], v[28:29] op_sel_hi:[1,0,1] neg_lo:[0,0,1] neg_hi:[0,0,1]
	v_pk_fma_f32 v[8:9], v[14:15], v[22:23], v[8:9] op_sel_hi:[1,0,1]
	v_pk_fma_f32 v[22:23], v[6:7], v[22:23], v[0:1] op_sel_hi:[1,0,1]
	v_or_b32_e32 v0, 32, v16
	v_cvt_pk_bf16_f32 v75, v22, v23
	v_lshlrev_b32_e32 v24, 16, v75
	v_and_b32_e32 v25, 0xffff0000, v75
	v_pk_add_f32 v[22:23], v[22:23], v[24:25] neg_lo:[0,1] neg_hi:[0,1]
	v_mul_f32_e32 v16, v27, v27
	v_cvt_pk_bf16_f32 v79, v22, v23
	v_fmamk_f32 v22, v16, 0xb94c1982, v215
	v_fmaak_f32 v22, v16, v22, 0xbe2aaa9d
	v_mul_f32_e32 v22, v16, v22
	v_fmac_f32_e32 v27, v27, v22
	v_fmamk_f32 v22, v16, 0x37d75334, v216
	v_fmaak_f32 v22, v16, v22, 0x3d2aabf7
	v_fmaak_f32 v22, v16, v22, 0xbf000004
	v_fma_f32 v16, v16, v22, 1.0
	v_and_b32_e32 v22, 1, v21
	v_lshlrev_b32_e32 v21, 30, v21
	v_ashrrev_i32_e32 v1, 31, v0
	v_cmp_eq_u32_e32 vcc, 0, v22
	v_and_b32_e32 v21, 0x80000000, v21
	v_cvt_pk_bf16_f32 v73, v8, v9
	v_lshlrev_b64 v[0:1], 6, v[0:1]
	v_cndmask_b32_e32 v16, v16, v27, vcc
	v_xor_b32_e32 v17, v17, v21
	v_lshlrev_b32_e32 v10, 16, v73
	v_and_b32_e32 v11, 0xffff0000, v73
	v_lshl_add_u64 v[2:3], s[48:49], 0, v[0:1]
	v_lshl_add_u64 v[0:1], s[50:51], 0, v[0:1]
	v_xor_b32_e32 v16, v17, v16
	v_pk_add_f32 v[8:9], v[8:9], v[10:11] neg_lo:[0,1] neg_hi:[0,1]
	v_lshl_add_u64 v[12:13], v[2:3], 0, v[96:97]
	v_lshl_add_u64 v[4:5], v[0:1], 0, v[96:97]
	v_cndmask_b32_e64 v16, v226, v16, s[40:41]
	v_cvt_pk_bf16_f32 v77, v8, v9
	global_load_dwordx4 v[0:3], v[4:5], off offset:16 nt
	global_load_dwordx4 v[8:11], v[4:5], off nt
	s_nop 0
	global_load_dwordx4 v[4:7], v[12:13], off offset:16 nt
	s_nop 0
	global_load_dwordx4 v[12:15], v[12:13], off nt
	v_mul_f32_e32 v118, v30, v16
	v_fma_f32 v22, v30, v31, -1.0
	v_mov_b32_e32 v23, v20
	v_pk_mul_f32 v[16:17], v[18:19], v[118:119] op_sel_hi:[0,1]
	v_pk_fma_f32 v[16:17], v[20:21], v[22:23], v[16:17] op_sel_hi:[0,1,1]
	v_div_scale_f32 v19, s[16:17], v17, v17, v16
	v_rcp_f32_e32 v23, v19
	v_mov_b32_e32 v119, v22
	s_lshl_b64 s[40:41], s[42:43], 12
	s_lshl_b32 s17, s20, 8
	v_fma_f32 v21, -v19, v23, 1.0
	v_fmac_f32_e32 v23, v21, v23
	v_div_scale_f32 v21, vcc, v16, v17, v16
	v_mul_f32_e32 v24, v21, v23
	v_fma_f32 v25, -v19, v24, v21
	v_fmac_f32_e32 v24, v25, v23
	v_fma_f32 v25, -v19, v24, v21
	v_mov_b32_e32 v21, v18
	v_pk_mul_f32 v[18:19], v[20:21], v[118:119]
	s_or_b32 s12, s40, s12
	v_sub_f32_e32 v20, v18, v19
	v_div_scale_f32 v21, s[20:21], v17, v17, v20
	v_mov_b32_e32 v19, s41
	v_or_b32_e32 v18, s12, v106
	v_readlane_b32 s20, v253, 21
	v_lshlrev_b64 v[18:19], 10, v[18:19]
	v_readlane_b32 s21, v253, 22
	v_lshlrev_b32_e32 v96, 1, v108
	v_rcp_f32_e32 v22, v21
	v_lshl_add_u64 v[18:19], s[20:21], 0, v[18:19]
	v_lshl_add_u64 v[18:19], v[18:19], 0, s[34:35]
	v_lshl_add_u64 v[18:19], v[18:19], 0, v[96:97]
	global_load_dwordx4 v[102:105], v[18:19], off nt
	v_div_fmas_f32 v18, v25, v23, v24
	v_div_fixup_f32 v16, v18, v17, v16
	v_fma_f32 v18, -v21, v22, 1.0
	v_fmac_f32_e32 v22, v18, v22
	v_div_scale_f32 v18, vcc, v20, v17, v20
	v_mul_f32_e32 v19, v18, v22
	v_fma_f32 v23, -v21, v19, v18
	v_fmac_f32_e32 v19, v23, v22
	v_fma_f32 v18, -v21, v19, v18
	v_div_fmas_f32 v18, v18, v22, v19
	v_div_fixup_f32 v18, v18, v17, v20
	s_or_b32 s40, s40, s17
	v_cvt_pk_bf16_f32 v67, v28, v29
	s_lshl_b32 s16, s46, 1
	v_lshlrev_b32_e32 v32, 16, v67
	v_and_b32_e32 v33, 0xffff0000, v67
	s_and_b32 s16, s16, 0x1e0
	v_pk_add_f32 v[28:29], v[28:29], v[32:33] neg_lo:[0,1] neg_hi:[0,1]
	v_mov_b32_e32 v116, 0
	v_mul_f32_e32 v109, v30, v31
	v_cvt_pk_bf16_f32 v71, v28, v29
	s_mov_b32 s25, 0xc2ce8ed0
	s_mov_b32 s24, 0x3fb8aa3b
	v_mov_b32_e32 v117, 0
	v_mov_b32_e32 v122, 0
	v_mov_b32_e32 v123, 0
	s_waitcnt vmcnt(3)
; __device__ __forceinline__ unsigned pk_bf16(float lo, float hi) { return pg8::cvt_pk_bf16(lo, hi); }
; template <bool PASS2> __device__ __forceinline__ void ssm2_pass(const Ctx& c, int l) {
;     ...
;           ssm2_coef(c, l, g, q, hi, arA, aiA, t0, t1); split_bf16x8(t0, Bh[0], Bl[0]); split_bf16x8(t1, Bh[2], Bl[2]);
;           ssm2_coef(c, l, g, 32 + q, hi, arB, aiB, t0, t1); split_bf16x8(t0, Bh[1], Bl[1]); split_bf16x8(t1, Bh[3], Bl[3]); }
;         bf16x8 Cb[8]; float dsk = 0.f;
;         if (PASS2) { const int h = lane & 15, kq = 4 * (lane >> 4); const size_t cb = ((size_t)(l * 16 + g) * 16 + h) * 64;
; #pragma unroll
;             for (int s_ = 0; s_ < 8; ++s_) { const float* src = (s_ < 4 ? c.inp(IN_CRE) : c.inp(IN_CIM)) + cb + 16 * (s_ & 3) + kq; const float sg = (s_ < 4) ? 1.f : -1.f;
;                 const f32x4 v0 = *(const f32x4*)src;
;                 const u32x4 w = {pk_bf16(sg * v0[0], sg * v0[0]), pk_bf16(sg * v0[1], sg * v0[1]), pk_bf16(sg * v0[2], sg * v0[2]), pk_bf16(sg * v0[3], sg * v0[3])};
;                 Cb[s_] = __builtin_bit_cast(bf16x8, w); }
;             dsk = c.inp(IN_DSKIP)[l * 256 + g * 16 + h]; }
;         float xAr = 0.f, xAi = 0.f, xBr = 0.f, xBi = 0.f;
;         if (PASS2 && tk > 0) {
;             float pAr = arA, pAi = aiA, pBr = arB, pBi = aiB;
; #pragma unroll
;             for (int k = 0; k < 8; ++k) { float nr = pAr * pAr - pAi * pAi, ni = 2.f * pAr * pAi; pAr = nr; pAi = ni; nr = pBr * pBr - pBi * pBi; ni = 2.f * pBr * pBi; pBr = nr; pBi = ni; }
;             for (int j = 0; j < tk; ++j) { const float2 eA = *(const float2*)(send + ((size_t)(bg * 16 + j) * 64 + q) * 2), eB = *(const float2*)(send + ((size_t)(bg * 16 + j) * 64 + 32 + q) * 2);
;                 float nr = pAr * xAr - pAi * xAi + eA.x, ni = pAr * xAi + pAi * xAr + eA.y; xAr = nr; xAi = ni;
;                 nr = pBr * xBr - pBi * xBi + eB.x; ni = pBr * xBi + pBi * xBr + eB.y; xBr = nr; xBi = ni; }
;         }
;         const size_t row0 = (size_t)b * SEQ + tk * 256;
;         const bf16_t* up = ZC + (row0 + q) * 512 + g * 16 + 8 * hi;
;         bf16x8 an = *(const bf16x8*)up;
; #pragma unroll 1
;         for (int blk = 0; blk < 8; ++blk) {
;             const bf16x8 a = an;
;             if (blk + 1 < 8) an = *(const bf16x8*)(up + (size_t)(blk + 1) * 32 * 512);
	v_pk_mul_f32 v[20:21], v[8:9], v[18:19] op_sel_hi:[1,0]
	s_waitcnt vmcnt(1)
	v_pk_fma_f32 v[20:21], v[12:13], v[16:17], v[20:21] op_sel_hi:[1,0,1] neg_lo:[0,0,1] neg_hi:[0,0,1]
	s_nop 0
	v_cvt_pk_bf16_f32 v80, v20, v21
	v_lshlrev_b32_e32 v22, 16, v80
	v_and_b32_e32 v23, 0xffff0000, v80
	v_pk_add_f32 v[20:21], v[20:21], v[22:23] neg_lo:[0,1] neg_hi:[0,1]
	v_pk_mul_f32 v[12:13], v[12:13], v[18:19] op_sel_hi:[1,0]
	v_cvt_pk_bf16_f32 v84, v20, v21
	v_pk_mul_f32 v[20:21], v[10:11], v[18:19] op_sel_hi:[1,0]
	v_pk_fma_f32 v[8:9], v[8:9], v[16:17], v[12:13] op_sel_hi:[1,0,1]
	v_pk_fma_f32 v[20:21], v[14:15], v[16:17], v[20:21] op_sel_hi:[1,0,1] neg_lo:[0,0,1] neg_hi:[0,0,1]
	v_cvt_pk_bf16_f32 v88, v8, v9
	v_cvt_pk_bf16_f32 v81, v20, v21
	v_lshlrev_b32_e32 v22, 16, v81
	v_and_b32_e32 v23, 0xffff0000, v81
	v_pk_add_f32 v[20:21], v[20:21], v[22:23] neg_lo:[0,1] neg_hi:[0,1]
	v_lshlrev_b32_e32 v12, 16, v88
	v_cvt_pk_bf16_f32 v85, v20, v21
	v_pk_mul_f32 v[20:21], v[0:1], v[18:19] op_sel_hi:[1,0]
	v_and_b32_e32 v13, 0xffff0000, v88
	v_pk_fma_f32 v[20:21], v[4:5], v[16:17], v[20:21] op_sel_hi:[1,0,1] neg_lo:[0,0,1] neg_hi:[0,0,1]
	v_pk_mul_f32 v[4:5], v[4:5], v[18:19] op_sel_hi:[1,0]
	v_cvt_pk_bf16_f32 v82, v20, v21
	v_pk_fma_f32 v[0:1], v[0:1], v[16:17], v[4:5] op_sel_hi:[1,0,1]
	v_lshlrev_b32_e32 v22, 16, v82
	v_cvt_pk_bf16_f32 v90, v0, v1
	v_lshlrev_b32_e32 v4, 16, v90
	v_and_b32_e32 v5, 0xffff0000, v90
	v_pk_add_f32 v[0:1], v[0:1], v[4:5] neg_lo:[0,1] neg_hi:[0,1]
	v_and_b32_e32 v23, 0xffff0000, v82
	v_cvt_pk_bf16_f32 v94, v0, v1
	v_pk_mul_f32 v[0:1], v[6:7], v[18:19] op_sel_hi:[1,0]
	v_pk_add_f32 v[20:21], v[20:21], v[22:23] neg_lo:[0,1] neg_hi:[0,1]
	v_pk_fma_f32 v[0:1], v[2:3], v[16:17], v[0:1] op_sel_hi:[1,0,1]
	v_pk_add_f32 v[8:9], v[8:9], v[12:13] neg_lo:[0,1] neg_hi:[0,1]
	v_cvt_pk_bf16_f32 v91, v0, v1
	v_cvt_pk_bf16_f32 v86, v20, v21
	v_pk_mul_f32 v[20:21], v[2:3], v[18:19] op_sel_hi:[1,0]
	v_cvt_pk_bf16_f32 v92, v8, v9
	v_pk_mul_f32 v[8:9], v[14:15], v[18:19] op_sel_hi:[1,0]
	v_lshlrev_b32_e32 v2, 16, v91
	v_and_b32_e32 v3, 0xffff0000, v91
	v_pk_fma_f32 v[20:21], v[6:7], v[16:17], v[20:21] op_sel_hi:[1,0,1] neg_lo:[0,0,1] neg_hi:[0,0,1]
	v_pk_fma_f32 v[8:9], v[10:11], v[16:17], v[8:9] op_sel_hi:[1,0,1]
	v_pk_add_f32 v[0:1], v[0:1], v[2:3] neg_lo:[0,1] neg_hi:[0,1]
	v_cvt_pk_bf16_f32 v83, v20, v21
	v_cvt_pk_bf16_f32 v89, v8, v9
	v_cvt_pk_bf16_f32 v95, v0, v1
	v_lshl_add_u64 v[0:1], s[40:41], 0, v[106:107]
	v_lshlrev_b32_e32 v22, 16, v83
	v_and_b32_e32 v23, 0xffff0000, v83
	v_lshlrev_b32_e32 v10, 16, v89
	v_and_b32_e32 v11, 0xffff0000, v89
	v_lshlrev_b64 v[0:1], 10, v[0:1]
	v_pk_add_f32 v[20:21], v[20:21], v[22:23] neg_lo:[0,1] neg_hi:[0,1]
	v_pk_add_f32 v[8:9], v[8:9], v[10:11] neg_lo:[0,1] neg_hi:[0,1]
	v_or_b32_e32 v0, s16, v0
	s_waitcnt vmcnt(0)
	v_mov_b64_e32 v[98:99], v[102:103]
	v_cvt_pk_bf16_f32 v87, v20, v21
	v_cvt_pk_bf16_f32 v93, v8, v9
	v_lshl_add_u64 v[120:121], v[112:113], 0, v[0:1]
	s_mov_b64 s[40:41], 0
	v_mov_b64_e32 v[100:101], v[104:105]
	s_cmp_eq_u32 s40, 0x38000
	s_cbranch_scc1 .LBB0_382
	s_branch .LBB0_381

; template <bool PASS2> __device__ __forceinline__ void ssm2_pass(const Ctx& c, int l) {
;     ...
;         for (int blk = 0; blk < 8; ++blk) {
;             const bf16x8 a = an;
;             if (blk + 1 < 8) an = *(const bf16x8*)(up + (size_t)(blk + 1) * 32 * 512);
.LBB0_381:
	v_lshl_add_u64 v[0:1], v[120:121], 0, s[40:41]
	global_load_dwordx4 v[98:101], v[0:1], off nt
